# m23 + indexer weight load hoisted above the Q-block wait + DSA attention prologue: K/V first-tile loads no longer wait for the Q loads
# speedup vs baseline: 1.0025x; 1.0025x over previous
; #define LAS __attribute__((address_space(3)))
; DEVI float bf2f(bf16_t v) { return __uint_as_float(((unsigned)v) << 16); }
; DEVI void indexer_phase(LAS unsigned char* lds, const bf16_t* EV, float* SC) {
;     ...
;         const int g = u & 63, b = u >> 6, m0 = b * SEQ + 32 * g, nt = (g >> 1) + 1;
;         { bf16x8 qv[8];
; #pragma unroll
;           for (int k = 0; k < 8; ++k) { const int idx = tid + 512 * k, row = idx >> 7, ch = idx & 127; qv[k] = *(const bf16x8*)(EV + (size_t)(m0 + row) * EVP + EV_QI + ch * 8); }
;           asm volatile("" : "+v"(qv[0]), "+v"(qv[1]), "+v"(qv[2]), "+v"(qv[3]), "+v"(qv[4]), "+v"(qv[5]), "+v"(qv[6]), "+v"(qv[7]));
; #pragma unroll
;           for (int k = 0; k < 8; ++k) { const int idx = tid + 512 * k, row = idx >> 7, ch = idx & 127; *(LAS bf16x8*)(lds + row * 2064 + ch * 16) = qv[k]; } }
;         wl[tid] = bf2f(EV[(size_t)(m0 + (tid & 31)) * EVP + EV_WI + (tid >> 5)]);
;         asm volatile("s_waitcnt lgkmcnt(0)" ::: "memory"); __builtin_amdgcn_s_barrier(); asm volatile("" ::: "memory");
;         for (int j = wid; j < nt; j += 8) {
;             bf16x8 kf[2][4];
; #pragma unroll
;             for (int hf = 0; hf < 2; ++hf)
; #pragma unroll
;                 for (int ks = 0; ks < 4; ++ks) kf[hf][ks] = *(const bf16x8*)(EV + (size_t)(b * SEQ + 64 * j + 32 * hf + r32) * EVP + EV_KI + 16 * ks + 8 * hi);
.LBB11_1270:
	s_lshl_b32 s6, s1, 5
	v_add_u32_e32 v4, s6, v145
	s_movk_i32 s7, 0x2c00
	v_mad_i64_i32 v[32:33], s[4:5], v4, s7, v[72:73]
	v_add_u32_e32 v4, s6, v146
	v_mad_i64_i32 v[28:29], s[4:5], v4, s7, v[72:73]
	v_add_u32_e32 v4, s6, v147
	v_mad_i64_i32 v[24:25], s[4:5], v4, s7, v[72:73]
	v_add_u32_e32 v4, s6, v148
	v_mad_i64_i32 v[20:21], s[4:5], v4, s7, v[72:73]
	v_add_u32_e32 v4, s6, v149
	v_mad_i64_i32 v[16:17], s[4:5], v4, s7, v[72:73]
	v_add_u32_e32 v4, s6, v150
	v_mad_i64_i32 v[12:13], s[4:5], v4, s7, v[72:73]
	v_add_u32_e32 v4, s6, v151
	v_mad_i64_i32 v[8:9], s[4:5], v4, s7, v[72:73]
	v_add_u32_e32 v4, s6, v152
	v_mad_i64_i32 v[4:5], s[4:5], v4, s7, v[72:73]
	global_load_dwordx4 v[4:7], v[4:5], off offset:2560
	s_nop 0
	global_load_dwordx4 v[8:11], v[8:9], off offset:2560
	s_nop 0
	global_load_dwordx4 v[12:15], v[12:13], off offset:2560
	s_nop 0
	global_load_dwordx4 v[16:19], v[16:17], off offset:2560
	s_nop 0
	global_load_dwordx4 v[20:23], v[20:21], off offset:2560
	s_nop 0
	global_load_dwordx4 v[24:27], v[24:25], off offset:2560
	s_nop 0
	global_load_dwordx4 v[28:31], v[28:29], off offset:2560
	s_nop 0
	global_load_dwordx4 v[32:35], v[32:33], off offset:2560
	v_mov_b64_e32 v[36:37], s[8:9]
	v_or_b32_e32 v38, s6, v140
	v_mad_i64_i32 v[36:37], s[4:5], v38, s7, v[36:37]
	v_lshl_add_u64 v[36:37], v[68:69], 1, v[36:37]
	v_add_co_u32_e32 v36, vcc, 0x1000, v36
	s_bfe_u32 s10, s1, 0x50001
	s_nop 0
	v_addc_co_u32_e32 v37, vcc, 0, v37, vcc
	v_cmp_ge_i32_e32 vcc, s10, v1
	global_load_ushort v36, v[36:37], off offset:640
	s_waitcnt vmcnt(1)
	ds_write_b128 v153, v[32:35]
	ds_write_b128 v154, v[28:31]
	ds_write_b128 v155, v[24:27]
	ds_write_b128 v156, v[20:23]
	ds_write_b128 v157, v[16:19]
	ds_write_b128 v158, v[12:15]
	ds_write_b128 v159, v[8:11]
	ds_write_b128 v160, v[4:7]
	s_waitcnt vmcnt(0)
	v_lshlrev_b32_e32 v4, 16, v36
	ds_write_b32 v141, v4
	s_waitcnt lgkmcnt(0)
	s_barrier
	s_and_saveexec_b64 s[4:5], vcc
	s_cbranch_execz .LBB11_1269
	v_or_b32_e32 v4, s6, v144
	v_or_b32_e32 v6, 1, v4
	v_ashrrev_i32_e32 v7, 31, v6
	v_lshlrev_b64 v[76:77], 13, v[6:7]
	v_or_b32_e32 v6, 2, v4
	v_ashrrev_i32_e32 v7, 31, v6
	v_lshlrev_b64 v[78:79], 13, v[6:7]
	v_or_b32_e32 v6, 3, v4
	v_ashrrev_i32_e32 v7, 31, v6
	v_lshlrev_b64 v[80:81], 13, v[6:7]
	v_or_b32_e32 v6, 8, v4
	v_ashrrev_i32_e32 v7, 31, v6
	v_lshlrev_b64 v[82:83], 13, v[6:7]
	v_or_b32_e32 v6, 9, v4
	v_ashrrev_i32_e32 v7, 31, v6
	v_lshlrev_b64 v[84:85], 13, v[6:7]
	v_or_b32_e32 v6, 10, v4
	v_ashrrev_i32_e32 v7, 31, v6
	v_lshlrev_b64 v[86:87], 13, v[6:7]
	v_or_b32_e32 v6, 11, v4
	v_ashrrev_i32_e32 v7, 31, v6
	v_lshlrev_b64 v[88:89], 13, v[6:7]
	v_or_b32_e32 v6, 16, v4
	v_ashrrev_i32_e32 v7, 31, v6
	v_lshlrev_b64 v[90:91], 13, v[6:7]
	v_or_b32_e32 v6, 17, v4
	v_ashrrev_i32_e32 v7, 31, v6
	v_lshlrev_b64 v[92:93], 13, v[6:7]
	v_or_b32_e32 v6, 18, v4
	v_ashrrev_i32_e32 v7, 31, v6
	v_lshlrev_b64 v[94:95], 13, v[6:7]
	v_or_b32_e32 v6, 19, v4
	v_ashrrev_i32_e32 v7, 31, v6
	v_lshlrev_b64 v[96:97], 13, v[6:7]
	v_or_b32_e32 v6, 24, v4
	v_ashrrev_i32_e32 v7, 31, v6
	v_lshlrev_b64 v[98:99], 13, v[6:7]
	v_or_b32_e32 v6, 25, v4
	v_ashrrev_i32_e32 v5, 31, v4
	v_ashrrev_i32_e32 v7, 31, v6
	v_lshlrev_b64 v[74:75], 13, v[4:5]
	v_lshlrev_b64 v[100:101], 13, v[6:7]
	v_or_b32_e32 v6, 26, v4
	v_or_b32_e32 v4, 27, v4
	s_and_b32 s7, s6, 0xfffff800
	v_ashrrev_i32_e32 v7, 31, v6
	v_ashrrev_i32_e32 v5, 31, v4
	v_or_b32_e32 v161, s7, v140
	v_lshlrev_b64 v[102:103], 13, v[6:7]
	v_lshlrev_b64 v[104:105], 13, v[4:5]
	s_mov_b64 s[6:7], 0
	v_mov_b32_e32 v162, v1

; #define LAS __attribute__((address_space(3)))
; DEVI int otid() { int t = threadIdx.x; asm volatile("" : "+v"(t)); return t; }
; DEVI int v_st(int k, int c) { const int kk = (k & ~0xC) | ((k & 4) << 1) | ((k & 8) >> 1); return ((kk >> 3) * 4 + (c >> 5)) * 512 + ((kk & 7) * 32 + (c & 31)) * 2; }
; DEVI int v_rd_base(int lane) { return ((lane & 3) << 3) | (((lane >> 2) & 3) << 6) | (((lane >> 4) & 1) << 5) | (((lane >> 5) & 1) << 8); }
; #define FA_SLOAD(jj) do { const size_t k0_ = (size_t)(jj) * 64; vs0 = *(const bf16x8*)(Vb + (k0_ + sr) * ldk + sc); vs1 = *(const bf16x8*)(Vb + (k0_ + 32 + sr) * ldk + sc); \
;         ks0 = *(const bf16x8*)(Kb + (k0_ + sr) * ldk + sc); ks1 = *(const bf16x8*)(Kb + (k0_ + 32 + sr) * ldk + sc); } while (0)
; template <int MODE>
; DEVI void attn_unit(LAS unsigned char* lds, const bf16_t* Qw, int ldq, const bf16_t* Kb, const bf16_t* Vb, int ldk, bf16_t* Ow, int ldo,
;                     int j_first, int ntiles, int jstep, int wj_lo, int wj_hi, int t0) {
;     const int tid = otid(), wid = tid >> 6, lane = tid & 63, r32 = lane & 31, hi = lane >> 5;
;     LAS unsigned char* V_lds = lds + OFF_V; LAS unsigned char* K_lds = lds + OFF_K;
;     LAS float* wsx = (LAS float*)(lds + OFF_WS) + wid * 64; LAS float* li_l = wsx; LAS float* al_l = wsx + 32;
;     LAS const float* bias2 = (LAS const float*)(lds + OFF_BIAS); LAS const u64* maskl = (LAS const u64*)(lds + OFF_MASK);
;     if (wid >= 4) __builtin_amdgcn_s_setprio(1);
;     float m_reg = -1e30f, l_reg = 0.f, carry = 0.f; bool mydone = false;
;     LAS unsigned* dflag = (LAS unsigned*)(lds + OFF_BIAS + 1024);
;     f32x16 o[4];
; #pragma unroll
;     for (int d = 0; d < 4; ++d) o[d] = (f32x16){0.f, 0.f, 0.f, 0.f, 0.f, 0.f, 0.f, 0.f, 0.f, 0.f, 0.f, 0.f, 0.f, 0.f, 0.f, 0.f};
;     bf16x8 qr[8];
;     const bf16_t* qp = Qw + (size_t)r32 * ldq + hi * 8;
;     if constexpr (MODE != M_STICK) {
; #pragma unroll
;       for (int d0 = 0; d0 < 8; ++d0) qr[d0] = *(const bf16x8*)(qp + d0 * 16); }
;     const int sr = tid >> 4, sc = (tid & 15) * 8, vst0 = v_st(sr, sc), vst1 = v_st(32 + sr, sc);
;     const int kst0 = FA_KSWZ(sr, sc * 2), kst1 = FA_KSWZ(32 + sr, sc * 2);
;     const int vb0 = (int)(uintptr_t)V_lds + v_rd_base(lane);
;     bf16x8 vs0, vs1, ks0, ks1;
;     ...
;     int j = j_first;
;     FA_SLOAD(j);
.LBB11_1651:
	s_waitcnt lgkmcnt(0)
	s_barrier
	v_mov_b32_e32 v4, v0
	s_movk_i32 s1, 0xff
	s_nop 0
	v_cmp_lt_i32_e32 vcc, s1, v4
	s_and_saveexec_b64 s[2:3], vcc
	v_readlane_b32 s9, v252, 30
	s_setprio 1
	s_or_b64 exec, exec, s[2:3]
	v_readlane_b32 s1, v253, 21
	s_lshl_b32 s1, s1, 5
	s_movk_i32 s4, 0x2c00
	s_and_b32 s1, s1, 0xfffff800
	v_mad_i64_i32 v[6:7], s[2:3], v160, s4, v[156:157]
	s_mul_hi_i32 s3, s1, 0x2c00
	s_mul_i32 s2, s1, 0x2c00
	v_and_b32_e32 v1, 31, v4
	v_bfe_u32 v165, v4, 5, 1
	v_lshl_add_u64 v[8:9], v[150:151], 0, s[2:3]
	v_mad_u64_u32 v[6:7], s[2:3], v1, s4, v[6:7]
	v_lshlrev_b32_e32 v162, 4, v165
	v_mov_b32_e32 v163, v3
	v_lshl_add_u64 v[6:7], v[6:7], 0, v[162:163]
	global_load_dwordx4 v[100:103], v[6:7], off
	global_load_dwordx4 v[104:107], v[6:7], off offset:32
	global_load_dwordx4 v[108:111], v[6:7], off offset:64
	global_load_dwordx4 v[112:115], v[6:7], off offset:96
	global_load_dwordx4 v[116:119], v[6:7], off offset:128
	global_load_dwordx4 v[120:123], v[6:7], off offset:160
	global_load_dwordx4 v[124:127], v[6:7], off offset:192
	global_load_dwordx4 v[128:131], v[6:7], off offset:224
	v_lshlrev_b32_e32 v13, 3, v4
	v_ashrrev_i32_e32 v12, 4, v4
	v_and_b32_e32 v6, 0x78, v13
	v_lshlrev_b32_e32 v6, 1, v6
	v_mad_i64_i32 v[8:9], s[2:3], v12, s4, v[8:9]
	v_mov_b32_e32 v7, v3
	v_and_b32_e32 v10, 0x3fffffc0, v4
	s_add_i32 s1, 0, 0x10000
	v_lshl_add_u64 v[8:9], v[8:9], 0, v[6:7]
	s_mov_b64 s[2:3], 0x58000
	v_lshl_add_u32 v167, v10, 2, s1
	v_lshl_add_u64 v[10:11], v[8:9], 0, s[2:3]
	global_load_dwordx4 v[132:135], v[8:9], off offset:2304
	global_load_dwordx4 v[136:139], v[8:9], off offset:2048
	global_load_dwordx4 v[140:143], v[10:11], off offset:2304
	global_load_dwordx4 v[144:147], v[10:11], off offset:2048
	v_and_b32_e32 v7, 0xfffff0, v12
	v_lshlrev_b32_e32 v10, 1, v12
	v_and_or_b32 v7, v10, 8, v7
	v_lshrrev_b32_e32 v7, 1, v7
	v_bfe_u32 v11, v13, 5, 2
	v_or_b32_e32 v7, v7, v11
	v_lshrrev_b32_e32 v10, 1, v12
	v_lshlrev_b32_e32 v163, 9, v7
	v_and_b32_e32 v7, 3, v12
	s_and_b32 s1, s9, 0xfffff800
	v_and_or_b32 v7, v10, 4, v7
	v_add_u32_e32 v10, 32, v12
	s_mul_hi_i32 s2, s1, 0x2c00
	v_and_b32_e32 v14, 0xfffff0, v10
	v_lshlrev_b32_e32 v15, 1, v10
	v_mov_b32_e32 v9, s2
	v_and_or_b32 v14, v15, 8, v14
	s_movk_i32 s2, 0x70
	v_and_b32_e32 v170, 48, v6
	v_lshrrev_b32_e32 v14, 1, v14
	v_bitop3_b32 v173, v6, v4, s2 bitop3:0x78
	v_lshlrev_b32_e32 v6, 4, v4
	v_or_b32_e32 v11, v14, v11
	v_and_b32_e32 v14, 0x70, v6
	v_bitop3_b32 v176, v162, v6, s2 bitop3:0x78
	s_movk_i32 s2, 0x60
	v_bitop3_b32 v179, v162, v14, s2 bitop3:0x36
	s_movk_i32 s2, 0x80
	v_bitop3_b32 v181, v162, v14, s2 bitop3:0x36
	s_movk_i32 s2, 0xa0
	v_bitop3_b32 v183, v162, v14, s2 bitop3:0x36
	s_movk_i32 s2, 0xc0
	v_lshlrev_b32_e32 v171, 9, v11
	v_lshlrev_b32_e32 v11, 1, v4
	v_bitop3_b32 v198, v162, v14, s2 bitop3:0x36
	s_movk_i32 s2, 0xe0
	v_and_b32_e32 v5, 63, v4
	s_mulk_i32 s1, 0x2c00
	v_and_b32_e32 v11, 32, v11
	v_bitop3_b32 v199, v162, v14, s2 bitop3:0x36
	s_movk_i32 s2, 0x118
	v_mov_b32_e32 v8, s1
	v_lshlrev_b32_e32 v175, 8, v1
	v_cmp_gt_u32_e64 s[40:41], 32, v5
	v_and_or_b32 v5, v13, s2, v11
	v_readlane_b32 s2, v252, 15
	v_readlane_b32 s1, v252, 29
	v_lshlrev_b32_e32 v174, 8, v10
	v_and_b32_e32 v10, 0xc0, v6
	v_lshl_add_u32 v200, v7, 6, 0
	v_add_u32_e32 v202, s2, v175
	v_mad_i64_i32 v[6:7], s[2:3], v12, s4, v[8:9]
	v_and_b32_e32 v4, 15, v4
	s_bfe_u32 s1, s1, 0x50001
	v_lshl_or_b32 v6, v4, 4, v6
	v_mov_b32_e32 v18, v3
	v_mov_b32_e32 v19, v3
	s_mul_i32 s1, s1, 0xb0000
	v_lshlrev_b32_e32 v172, 8, v12
	v_bitop3_b32 v177, v162, v14, 32 bitop3:0x36
	v_bitop3_b32 v178, v162, v14, 64 bitop3:0x36
	v_lshlrev_b32_e32 v164, 2, v165
	v_add3_u32 v201, v10, 0, v5
	v_lshl_add_u64 v[168:169], v[148:149], 0, v[6:7]
	v_mov_b32_e32 v4, v3
	v_mov_b32_e32 v5, v3
	v_mov_b32_e32 v6, v3
	v_mov_b32_e32 v7, v3
	v_mov_b32_e32 v8, v3
	v_mov_b32_e32 v9, v3
	v_mov_b32_e32 v10, v3
	v_mov_b32_e32 v11, v3
	v_mov_b32_e32 v12, v3
	v_mov_b32_e32 v13, v3
	v_mov_b32_e32 v14, v3
	v_mov_b32_e32 v15, v3
	v_mov_b32_e32 v16, v3
	v_mov_b32_e32 v17, v3
	v_mov_b64_e32 v[66:67], v[18:19]
	v_mov_b64_e32 v[50:51], v[18:19]
	v_mov_b64_e32 v[34:35], v[18:19]
	v_ashrrev_i32_e32 v161, 31, v160
	s_add_u32 s1, s1, 0xb0000
	v_lshl_add_u32 v180, v1, 2, v167
	v_or_b32_e32 v166, 32, v164
	s_mov_b32 s6, 0
	v_mov_b32_e32 v203, 0
	v_mov_b32_e32 v206, 0xf149f2ca
	s_mov_b64 s[2:3], 0
	v_mov_b64_e32 v[64:65], v[16:17]
	v_mov_b64_e32 v[62:63], v[14:15]
	v_mov_b64_e32 v[60:61], v[12:13]
	v_mov_b64_e32 v[58:59], v[10:11]
	v_mov_b64_e32 v[56:57], v[8:9]
	v_mov_b64_e32 v[54:55], v[6:7]
	v_mov_b64_e32 v[52:53], v[4:5]
	v_mov_b64_e32 v[48:49], v[16:17]
	v_mov_b64_e32 v[46:47], v[14:15]
	v_mov_b64_e32 v[44:45], v[12:13]
	v_mov_b64_e32 v[42:43], v[10:11]
	v_mov_b64_e32 v[40:41], v[8:9]
	v_mov_b64_e32 v[38:39], v[6:7]
	v_mov_b64_e32 v[36:37], v[4:5]
	v_mov_b64_e32 v[32:33], v[16:17]
	v_mov_b64_e32 v[30:31], v[14:15]
	v_mov_b64_e32 v[28:29], v[12:13]
	v_mov_b64_e32 v[26:27], v[10:11]
	v_mov_b64_e32 v[24:25], v[8:9]
	v_mov_b64_e32 v[22:23], v[6:7]
	v_mov_b64_e32 v[20:21], v[4:5]
	s_mov_b32 s7, 0
